# v34: S5B epilogue (gelu(acc+YIN) -> YG) rewritten with YIN loads 4 pieces ahead and counted waits instead of 16 load-wait(0)-store round trips
# baseline (speedup 1.0000x reference)
.LBB0_1212:
	v_add_u32_e32 v145, s33, v153
	v_add_u32_e32 v142, s20, v145
	v_ashrrev_i32_e32 v143, 31, v142
	v_or_b32_e32 v158, s11, v154
	v_lshlrev_b64 v[142:143], 10, v[142:143]
	v_lshl_add_u64 v[142:143], s[4:5], 0, v[142:143]
	v_lshlrev_b32_e32 v0, 2, v158
	v_lshl_add_u64 v[150:151], v[142:143], 0, v[0:1]
	s_lshl_b32 s0, s10, 4
	s_ashr_i32 s1, s0, 31
	v_lshrrev_b32_e32 v144, 4, v158
	v_lshlrev_b32_e32 v159, 4, v145
	v_and_b32_e32 v142, 8, v152
	s_lshl_b64 s[0:1], s[0:1], 1
	v_or_b32_e32 v152, v159, v144
	s_add_u32 s0, s92, s0
	v_ashrrev_i32_e32 v153, 31, v152
	s_addc_u32 s1, s93, s1
	v_lshlrev_b64 v[152:153], 10, v[152:153]
	v_mov_b32_e32 v143, v1
	v_lshlrev_b32_e32 v142, 1, v142
	v_lshl_add_u64 v[152:153], s[0:1], 0, v[152:153]
	v_lshl_add_u64 v[152:153], v[152:153], 0, v[142:143]
	s_mov_b32 s28, s96
	v_mov_b32_e32 v244, v150
	v_mov_b32_e32 v245, v151
	v_add_co_u32_e32 v246, vcc, 0x2000, v152
	v_addc_co_u32_e32 v247, vcc, 0, v153, vcc
	global_load_dwordx4 v[196:199], v[244:245], off
	global_load_dwordx4 v[200:203], v[244:245], off offset:16
	global_load_dwordx4 v[204:207], v[244:245], off offset:512
	global_load_dwordx4 v[208:211], v[244:245], off offset:528
	v_add_co_u32_e32 v244, vcc, 0x4000, v244
	v_addc_co_u32_e32 v245, vcc, 0, v245, vcc
	global_load_dwordx4 v[212:215], v[244:245], off
	global_load_dwordx4 v[216:219], v[244:245], off offset:16
	global_load_dwordx4 v[220:223], v[244:245], off offset:512
	global_load_dwordx4 v[224:227], v[244:245], off offset:528
	v_add_co_u32_e32 v244, vcc, 0x4000, v244
	v_addc_co_u32_e32 v245, vcc, 0, v245, vcc
	s_waitcnt vmcnt(6)
	v_pk_add_f32 v[128:129], v[128:129], v[198:199]
	v_pk_add_f32 v[126:127], v[126:127], v[196:197]
	v_pk_add_f32 v[124:125], v[124:125], v[202:203]
	v_pk_add_f32 v[122:123], v[122:123], v[200:201]
	v_mul_f32_e32 v228, 0x3d372713, v126
	v_mul_f32_e32 v229, 0x3d372713, v127
	v_mul_f32_e32 v230, 0x3d372713, v122
	v_mul_f32_e32 v231, 0x3d372713, v123
	v_mul_f32_e32 v232, 0x3d372713, v128
	v_mul_f32_e32 v233, 0x3d372713, v129
	v_mul_f32_e32 v234, 0x3d372713, v124
	v_mul_f32_e32 v235, 0x3d372713, v125
	v_mul_f32_e32 v228, v126, v228
	v_mul_f32_e32 v229, v127, v229
	v_mul_f32_e32 v230, v122, v230
	v_mul_f32_e32 v231, v123, v231
	v_mul_f32_e32 v232, v128, v232
	v_mul_f32_e32 v233, v129, v233
	v_mul_f32_e32 v234, v124, v234
	v_mul_f32_e32 v235, v125, v235
	v_fma_f32 v228, v126, v228, v126
	v_fma_f32 v229, v127, v229, v127
	v_fma_f32 v230, v122, v230, v122
	v_fma_f32 v231, v123, v231, v123
	v_fma_f32 v232, v128, v232, v128
	v_fma_f32 v233, v129, v233, v129
	v_fma_f32 v234, v124, v234, v124
	v_fma_f32 v235, v125, v235, v125
	v_mul_f32_e32 v228, 0xbfcc422a, v228
	v_mul_f32_e32 v229, 0xbfcc422a, v229
	v_mul_f32_e32 v230, 0xbfcc422a, v230
	v_mul_f32_e32 v231, 0xbfcc422a, v231
	v_mul_f32_e32 v232, 0xbfcc422a, v232
	v_mul_f32_e32 v233, 0xbfcc422a, v233
	v_mul_f32_e32 v234, 0xbfcc422a, v234
	v_mul_f32_e32 v235, 0xbfcc422a, v235
	v_mul_f32_e32 v228, 0x3fb8aa3b, v228
	v_mul_f32_e32 v229, 0x3fb8aa3b, v229
	v_mul_f32_e32 v230, 0x3fb8aa3b, v230
	v_mul_f32_e32 v231, 0x3fb8aa3b, v231
	v_mul_f32_e32 v232, 0x3fb8aa3b, v232
	v_mul_f32_e32 v233, 0x3fb8aa3b, v233
	v_mul_f32_e32 v234, 0x3fb8aa3b, v234
	v_mul_f32_e32 v235, 0x3fb8aa3b, v235
	v_exp_f32_e32 v228, v228
	v_exp_f32_e32 v229, v229
	v_exp_f32_e32 v230, v230
	v_exp_f32_e32 v231, v231
	v_exp_f32_e32 v232, v232
	v_exp_f32_e32 v233, v233
	v_exp_f32_e32 v234, v234
	v_exp_f32_e32 v235, v235
	v_add_f32_e32 v228, 1.0, v228
	v_add_f32_e32 v229, 1.0, v229
	v_add_f32_e32 v230, 1.0, v230
	v_add_f32_e32 v231, 1.0, v231
	v_add_f32_e32 v232, 1.0, v232
	v_add_f32_e32 v233, 1.0, v233
	v_add_f32_e32 v234, 1.0, v234
	v_add_f32_e32 v235, 1.0, v235
	v_rcp_f32_e32 v228, v228
	v_rcp_f32_e32 v229, v229
	v_rcp_f32_e32 v230, v230
	v_rcp_f32_e32 v231, v231
	v_rcp_f32_e32 v232, v232
	v_rcp_f32_e32 v233, v233
	v_rcp_f32_e32 v234, v234
	v_rcp_f32_e32 v235, v235
	v_pk_mul_f32 v[126:127], v[126:127], v[228:229]
	v_pk_mul_f32 v[122:123], v[122:123], v[230:231]
	v_pk_mul_f32 v[128:129], v[128:129], v[232:233]
	v_pk_mul_f32 v[124:125], v[124:125], v[234:235]
	v_cvt_pk_bf16_f32 v236, v126, v127
	v_cvt_pk_bf16_f32 v237, v128, v129
	v_cvt_pk_bf16_f32 v238, v122, v123
	v_cvt_pk_bf16_f32 v239, v124, v125
	global_store_dwordx4 v[152:153], v[236:239], off
	global_load_dwordx4 v[196:199], v[244:245], off
	global_load_dwordx4 v[200:203], v[244:245], off offset:16
	s_waitcnt vmcnt(7)
	v_pk_add_f32 v[120:121], v[120:121], v[206:207]
	v_pk_add_f32 v[118:119], v[118:119], v[204:205]
	v_pk_add_f32 v[116:117], v[116:117], v[210:211]
	v_pk_add_f32 v[114:115], v[114:115], v[208:209]
	v_mul_f32_e32 v228, 0x3d372713, v118
	v_mul_f32_e32 v229, 0x3d372713, v119
	v_mul_f32_e32 v230, 0x3d372713, v114
	v_mul_f32_e32 v231, 0x3d372713, v115
	v_mul_f32_e32 v232, 0x3d372713, v120
	v_mul_f32_e32 v233, 0x3d372713, v121
	v_mul_f32_e32 v234, 0x3d372713, v116
	v_mul_f32_e32 v235, 0x3d372713, v117
	v_mul_f32_e32 v228, v118, v228
	v_mul_f32_e32 v229, v119, v229
	v_mul_f32_e32 v230, v114, v230
	v_mul_f32_e32 v231, v115, v231
	v_mul_f32_e32 v232, v120, v232
	v_mul_f32_e32 v233, v121, v233
	v_mul_f32_e32 v234, v116, v234
	v_mul_f32_e32 v235, v117, v235
	v_fma_f32 v228, v118, v228, v118
	v_fma_f32 v229, v119, v229, v119
	v_fma_f32 v230, v114, v230, v114
	v_fma_f32 v231, v115, v231, v115
	v_fma_f32 v232, v120, v232, v120
	v_fma_f32 v233, v121, v233, v121
	v_fma_f32 v234, v116, v234, v116
	v_fma_f32 v235, v117, v235, v117
	v_mul_f32_e32 v228, 0xbfcc422a, v228
	v_mul_f32_e32 v229, 0xbfcc422a, v229
	v_mul_f32_e32 v230, 0xbfcc422a, v230
	v_mul_f32_e32 v231, 0xbfcc422a, v231
	v_mul_f32_e32 v232, 0xbfcc422a, v232
	v_mul_f32_e32 v233, 0xbfcc422a, v233
	v_mul_f32_e32 v234, 0xbfcc422a, v234
	v_mul_f32_e32 v235, 0xbfcc422a, v235
	v_mul_f32_e32 v228, 0x3fb8aa3b, v228
	v_mul_f32_e32 v229, 0x3fb8aa3b, v229
	v_mul_f32_e32 v230, 0x3fb8aa3b, v230
	v_mul_f32_e32 v231, 0x3fb8aa3b, v231
	v_mul_f32_e32 v232, 0x3fb8aa3b, v232
	v_mul_f32_e32 v233, 0x3fb8aa3b, v233
	v_mul_f32_e32 v234, 0x3fb8aa3b, v234
	v_mul_f32_e32 v235, 0x3fb8aa3b, v235
	v_exp_f32_e32 v228, v228
	v_exp_f32_e32 v229, v229
	v_exp_f32_e32 v230, v230
	v_exp_f32_e32 v231, v231
	v_exp_f32_e32 v232, v232
	v_exp_f32_e32 v233, v233
	v_exp_f32_e32 v234, v234
	v_exp_f32_e32 v235, v235
	v_add_f32_e32 v228, 1.0, v228
	v_add_f32_e32 v229, 1.0, v229
	v_add_f32_e32 v230, 1.0, v230
	v_add_f32_e32 v231, 1.0, v231
	v_add_f32_e32 v232, 1.0, v232
	v_add_f32_e32 v233, 1.0, v233
	v_add_f32_e32 v234, 1.0, v234
	v_add_f32_e32 v235, 1.0, v235
	v_rcp_f32_e32 v228, v228
	v_rcp_f32_e32 v229, v229
	v_rcp_f32_e32 v230, v230
	v_rcp_f32_e32 v231, v231
	v_rcp_f32_e32 v232, v232
	v_rcp_f32_e32 v233, v233
	v_rcp_f32_e32 v234, v234
	v_rcp_f32_e32 v235, v235
	v_pk_mul_f32 v[118:119], v[118:119], v[228:229]
	v_pk_mul_f32 v[114:115], v[114:115], v[230:231]
	v_pk_mul_f32 v[120:121], v[120:121], v[232:233]
	v_pk_mul_f32 v[116:117], v[116:117], v[234:235]
	v_cvt_pk_bf16_f32 v236, v118, v119
	v_cvt_pk_bf16_f32 v237, v120, v121
	v_cvt_pk_bf16_f32 v238, v114, v115
	v_cvt_pk_bf16_f32 v239, v116, v117
	global_store_dwordx4 v[246:247], v[236:239], off
	v_add_co_u32_e32 v152, vcc, 0x40000, v152
	v_addc_co_u32_e32 v153, vcc, 0, v153, vcc
	v_add_co_u32_e32 v246, vcc, 0x40000, v246
	v_addc_co_u32_e32 v247, vcc, 0, v247, vcc
	global_load_dwordx4 v[204:207], v[244:245], off offset:512
	global_load_dwordx4 v[208:211], v[244:245], off offset:528
	v_add_co_u32_e32 v244, vcc, 0x4000, v244
	v_addc_co_u32_e32 v245, vcc, 0, v245, vcc
	s_waitcnt vmcnt(8)
	v_pk_add_f32 v[112:113], v[112:113], v[214:215]
	v_pk_add_f32 v[110:111], v[110:111], v[212:213]
	v_pk_add_f32 v[108:109], v[108:109], v[218:219]
	v_pk_add_f32 v[106:107], v[106:107], v[216:217]
	v_mul_f32_e32 v228, 0x3d372713, v110
	v_mul_f32_e32 v229, 0x3d372713, v111
	v_mul_f32_e32 v230, 0x3d372713, v106
	v_mul_f32_e32 v231, 0x3d372713, v107
	v_mul_f32_e32 v232, 0x3d372713, v112
	v_mul_f32_e32 v233, 0x3d372713, v113
	v_mul_f32_e32 v234, 0x3d372713, v108
	v_mul_f32_e32 v235, 0x3d372713, v109
	v_mul_f32_e32 v228, v110, v228
	v_mul_f32_e32 v229, v111, v229
	v_mul_f32_e32 v230, v106, v230
	v_mul_f32_e32 v231, v107, v231
	v_mul_f32_e32 v232, v112, v232
	v_mul_f32_e32 v233, v113, v233
	v_mul_f32_e32 v234, v108, v234
	v_mul_f32_e32 v235, v109, v235
	v_fma_f32 v228, v110, v228, v110
	v_fma_f32 v229, v111, v229, v111
	v_fma_f32 v230, v106, v230, v106
	v_fma_f32 v231, v107, v231, v107
	v_fma_f32 v232, v112, v232, v112
	v_fma_f32 v233, v113, v233, v113
	v_fma_f32 v234, v108, v234, v108
	v_fma_f32 v235, v109, v235, v109
	v_mul_f32_e32 v228, 0xbfcc422a, v228
	v_mul_f32_e32 v229, 0xbfcc422a, v229
	v_mul_f32_e32 v230, 0xbfcc422a, v230
	v_mul_f32_e32 v231, 0xbfcc422a, v231
	v_mul_f32_e32 v232, 0xbfcc422a, v232
	v_mul_f32_e32 v233, 0xbfcc422a, v233
	v_mul_f32_e32 v234, 0xbfcc422a, v234
	v_mul_f32_e32 v235, 0xbfcc422a, v235
	v_mul_f32_e32 v228, 0x3fb8aa3b, v228
	v_mul_f32_e32 v229, 0x3fb8aa3b, v229
	v_mul_f32_e32 v230, 0x3fb8aa3b, v230
	v_mul_f32_e32 v231, 0x3fb8aa3b, v231
	v_mul_f32_e32 v232, 0x3fb8aa3b, v232
	v_mul_f32_e32 v233, 0x3fb8aa3b, v233
	v_mul_f32_e32 v234, 0x3fb8aa3b, v234
	v_mul_f32_e32 v235, 0x3fb8aa3b, v235
	v_exp_f32_e32 v228, v228
	v_exp_f32_e32 v229, v229
	v_exp_f32_e32 v230, v230
	v_exp_f32_e32 v231, v231
	v_exp_f32_e32 v232, v232
	v_exp_f32_e32 v233, v233
	v_exp_f32_e32 v234, v234
	v_exp_f32_e32 v235, v235
	v_add_f32_e32 v228, 1.0, v228
	v_add_f32_e32 v229, 1.0, v229
	v_add_f32_e32 v230, 1.0, v230
	v_add_f32_e32 v231, 1.0, v231
	v_add_f32_e32 v232, 1.0, v232
	v_add_f32_e32 v233, 1.0, v233
	v_add_f32_e32 v234, 1.0, v234
	v_add_f32_e32 v235, 1.0, v235
	v_rcp_f32_e32 v228, v228
	v_rcp_f32_e32 v229, v229
	v_rcp_f32_e32 v230, v230
	v_rcp_f32_e32 v231, v231
	v_rcp_f32_e32 v232, v232
	v_rcp_f32_e32 v233, v233
	v_rcp_f32_e32 v234, v234
	v_rcp_f32_e32 v235, v235
	v_pk_mul_f32 v[110:111], v[110:111], v[228:229]
	v_pk_mul_f32 v[106:107], v[106:107], v[230:231]
	v_pk_mul_f32 v[112:113], v[112:113], v[232:233]
	v_pk_mul_f32 v[108:109], v[108:109], v[234:235]
	v_cvt_pk_bf16_f32 v236, v110, v111
	v_cvt_pk_bf16_f32 v237, v112, v113
	v_cvt_pk_bf16_f32 v238, v106, v107
	v_cvt_pk_bf16_f32 v239, v108, v109
	global_store_dwordx4 v[152:153], v[236:239], off
	global_load_dwordx4 v[212:215], v[244:245], off
	global_load_dwordx4 v[216:219], v[244:245], off offset:16
	s_waitcnt vmcnt(9)
	v_pk_add_f32 v[104:105], v[104:105], v[222:223]
	v_pk_add_f32 v[102:103], v[102:103], v[220:221]
	v_pk_add_f32 v[100:101], v[100:101], v[226:227]
	v_pk_add_f32 v[98:99], v[98:99], v[224:225]
	v_mul_f32_e32 v228, 0x3d372713, v102
	v_mul_f32_e32 v229, 0x3d372713, v103
	v_mul_f32_e32 v230, 0x3d372713, v98
	v_mul_f32_e32 v231, 0x3d372713, v99
	v_mul_f32_e32 v232, 0x3d372713, v104
	v_mul_f32_e32 v233, 0x3d372713, v105
	v_mul_f32_e32 v234, 0x3d372713, v100
	v_mul_f32_e32 v235, 0x3d372713, v101
	v_mul_f32_e32 v228, v102, v228
	v_mul_f32_e32 v229, v103, v229
	v_mul_f32_e32 v230, v98, v230
	v_mul_f32_e32 v231, v99, v231
	v_mul_f32_e32 v232, v104, v232
	v_mul_f32_e32 v233, v105, v233
	v_mul_f32_e32 v234, v100, v234
	v_mul_f32_e32 v235, v101, v235
	v_fma_f32 v228, v102, v228, v102
	v_fma_f32 v229, v103, v229, v103
	v_fma_f32 v230, v98, v230, v98
	v_fma_f32 v231, v99, v231, v99
	v_fma_f32 v232, v104, v232, v104
	v_fma_f32 v233, v105, v233, v105
	v_fma_f32 v234, v100, v234, v100
	v_fma_f32 v235, v101, v235, v101
	v_mul_f32_e32 v228, 0xbfcc422a, v228
	v_mul_f32_e32 v229, 0xbfcc422a, v229
	v_mul_f32_e32 v230, 0xbfcc422a, v230
	v_mul_f32_e32 v231, 0xbfcc422a, v231
	v_mul_f32_e32 v232, 0xbfcc422a, v232
	v_mul_f32_e32 v233, 0xbfcc422a, v233
	v_mul_f32_e32 v234, 0xbfcc422a, v234
	v_mul_f32_e32 v235, 0xbfcc422a, v235
	v_mul_f32_e32 v228, 0x3fb8aa3b, v228
	v_mul_f32_e32 v229, 0x3fb8aa3b, v229
	v_mul_f32_e32 v230, 0x3fb8aa3b, v230
	v_mul_f32_e32 v231, 0x3fb8aa3b, v231
	v_mul_f32_e32 v232, 0x3fb8aa3b, v232
	v_mul_f32_e32 v233, 0x3fb8aa3b, v233
	v_mul_f32_e32 v234, 0x3fb8aa3b, v234
	v_mul_f32_e32 v235, 0x3fb8aa3b, v235
	v_exp_f32_e32 v228, v228
	v_exp_f32_e32 v229, v229
	v_exp_f32_e32 v230, v230
	v_exp_f32_e32 v231, v231
	v_exp_f32_e32 v232, v232
	v_exp_f32_e32 v233, v233
	v_exp_f32_e32 v234, v234
	v_exp_f32_e32 v235, v235
	v_add_f32_e32 v228, 1.0, v228
	v_add_f32_e32 v229, 1.0, v229
	v_add_f32_e32 v230, 1.0, v230
	v_add_f32_e32 v231, 1.0, v231
	v_add_f32_e32 v232, 1.0, v232
	v_add_f32_e32 v233, 1.0, v233
	v_add_f32_e32 v234, 1.0, v234
	v_add_f32_e32 v235, 1.0, v235
	v_rcp_f32_e32 v228, v228
	v_rcp_f32_e32 v229, v229
	v_rcp_f32_e32 v230, v230
	v_rcp_f32_e32 v231, v231
	v_rcp_f32_e32 v232, v232
	v_rcp_f32_e32 v233, v233
	v_rcp_f32_e32 v234, v234
	v_rcp_f32_e32 v235, v235
	v_pk_mul_f32 v[102:103], v[102:103], v[228:229]
	v_pk_mul_f32 v[98:99], v[98:99], v[230:231]
	v_pk_mul_f32 v[104:105], v[104:105], v[232:233]
	v_pk_mul_f32 v[100:101], v[100:101], v[234:235]
	v_cvt_pk_bf16_f32 v236, v102, v103
	v_cvt_pk_bf16_f32 v237, v104, v105
	v_cvt_pk_bf16_f32 v238, v98, v99
	v_cvt_pk_bf16_f32 v239, v100, v101
	global_store_dwordx4 v[246:247], v[236:239], off
	v_add_co_u32_e32 v152, vcc, 0x40000, v152
	v_addc_co_u32_e32 v153, vcc, 0, v153, vcc
	v_add_co_u32_e32 v246, vcc, 0x40000, v246
	v_addc_co_u32_e32 v247, vcc, 0, v247, vcc
	global_load_dwordx4 v[220:223], v[244:245], off offset:512
	global_load_dwordx4 v[224:227], v[244:245], off offset:528
	v_add_co_u32_e32 v244, vcc, 0x14000, v244
	v_addc_co_u32_e32 v245, vcc, 0, v245, vcc
	s_waitcnt vmcnt(9)
	v_pk_add_f32 v[96:97], v[96:97], v[198:199]
	v_pk_add_f32 v[94:95], v[94:95], v[196:197]
	v_pk_add_f32 v[92:93], v[92:93], v[202:203]
	v_pk_add_f32 v[90:91], v[90:91], v[200:201]
	v_mul_f32_e32 v228, 0x3d372713, v94
	v_mul_f32_e32 v229, 0x3d372713, v95
	v_mul_f32_e32 v230, 0x3d372713, v90
	v_mul_f32_e32 v231, 0x3d372713, v91
	v_mul_f32_e32 v232, 0x3d372713, v96
	v_mul_f32_e32 v233, 0x3d372713, v97
	v_mul_f32_e32 v234, 0x3d372713, v92
	v_mul_f32_e32 v235, 0x3d372713, v93
	v_mul_f32_e32 v228, v94, v228
	v_mul_f32_e32 v229, v95, v229
	v_mul_f32_e32 v230, v90, v230
	v_mul_f32_e32 v231, v91, v231
	v_mul_f32_e32 v232, v96, v232
	v_mul_f32_e32 v233, v97, v233
	v_mul_f32_e32 v234, v92, v234
	v_mul_f32_e32 v235, v93, v235
	v_fma_f32 v228, v94, v228, v94
	v_fma_f32 v229, v95, v229, v95
	v_fma_f32 v230, v90, v230, v90
	v_fma_f32 v231, v91, v231, v91
	v_fma_f32 v232, v96, v232, v96
	v_fma_f32 v233, v97, v233, v97
	v_fma_f32 v234, v92, v234, v92
	v_fma_f32 v235, v93, v235, v93
	v_mul_f32_e32 v228, 0xbfcc422a, v228
	v_mul_f32_e32 v229, 0xbfcc422a, v229
	v_mul_f32_e32 v230, 0xbfcc422a, v230
	v_mul_f32_e32 v231, 0xbfcc422a, v231
	v_mul_f32_e32 v232, 0xbfcc422a, v232
	v_mul_f32_e32 v233, 0xbfcc422a, v233
	v_mul_f32_e32 v234, 0xbfcc422a, v234
	v_mul_f32_e32 v235, 0xbfcc422a, v235
	v_mul_f32_e32 v228, 0x3fb8aa3b, v228
	v_mul_f32_e32 v229, 0x3fb8aa3b, v229
	v_mul_f32_e32 v230, 0x3fb8aa3b, v230
	v_mul_f32_e32 v231, 0x3fb8aa3b, v231
	v_mul_f32_e32 v232, 0x3fb8aa3b, v232
	v_mul_f32_e32 v233, 0x3fb8aa3b, v233
	v_mul_f32_e32 v234, 0x3fb8aa3b, v234
	v_mul_f32_e32 v235, 0x3fb8aa3b, v235
	v_exp_f32_e32 v228, v228
	v_exp_f32_e32 v229, v229
	v_exp_f32_e32 v230, v230
	v_exp_f32_e32 v231, v231
	v_exp_f32_e32 v232, v232
	v_exp_f32_e32 v233, v233
	v_exp_f32_e32 v234, v234
	v_exp_f32_e32 v235, v235
	v_add_f32_e32 v228, 1.0, v228
	v_add_f32_e32 v229, 1.0, v229
	v_add_f32_e32 v230, 1.0, v230
	v_add_f32_e32 v231, 1.0, v231
	v_add_f32_e32 v232, 1.0, v232
	v_add_f32_e32 v233, 1.0, v233
	v_add_f32_e32 v234, 1.0, v234
	v_add_f32_e32 v235, 1.0, v235
	v_rcp_f32_e32 v228, v228
	v_rcp_f32_e32 v229, v229
	v_rcp_f32_e32 v230, v230
	v_rcp_f32_e32 v231, v231
	v_rcp_f32_e32 v232, v232
	v_rcp_f32_e32 v233, v233
	v_rcp_f32_e32 v234, v234
	v_rcp_f32_e32 v235, v235
	v_pk_mul_f32 v[94:95], v[94:95], v[228:229]
	v_pk_mul_f32 v[90:91], v[90:91], v[230:231]
	v_pk_mul_f32 v[96:97], v[96:97], v[232:233]
	v_pk_mul_f32 v[92:93], v[92:93], v[234:235]
	v_cvt_pk_bf16_f32 v236, v94, v95
	v_cvt_pk_bf16_f32 v237, v96, v97
	v_cvt_pk_bf16_f32 v238, v90, v91
	v_cvt_pk_bf16_f32 v239, v92, v93
	global_store_dwordx4 v[152:153], v[236:239], off
	global_load_dwordx4 v[196:199], v[244:245], off
	global_load_dwordx4 v[200:203], v[244:245], off offset:16
	s_waitcnt vmcnt(9)
	v_pk_add_f32 v[88:89], v[88:89], v[206:207]
	v_pk_add_f32 v[86:87], v[86:87], v[204:205]
	v_pk_add_f32 v[84:85], v[84:85], v[210:211]
	v_pk_add_f32 v[82:83], v[82:83], v[208:209]
	v_mul_f32_e32 v228, 0x3d372713, v86
	v_mul_f32_e32 v229, 0x3d372713, v87
	v_mul_f32_e32 v230, 0x3d372713, v82
	v_mul_f32_e32 v231, 0x3d372713, v83
	v_mul_f32_e32 v232, 0x3d372713, v88
	v_mul_f32_e32 v233, 0x3d372713, v89
	v_mul_f32_e32 v234, 0x3d372713, v84
	v_mul_f32_e32 v235, 0x3d372713, v85
	v_mul_f32_e32 v228, v86, v228
	v_mul_f32_e32 v229, v87, v229
	v_mul_f32_e32 v230, v82, v230
	v_mul_f32_e32 v231, v83, v231
	v_mul_f32_e32 v232, v88, v232
	v_mul_f32_e32 v233, v89, v233
	v_mul_f32_e32 v234, v84, v234
	v_mul_f32_e32 v235, v85, v235
	v_fma_f32 v228, v86, v228, v86
	v_fma_f32 v229, v87, v229, v87
	v_fma_f32 v230, v82, v230, v82
	v_fma_f32 v231, v83, v231, v83
	v_fma_f32 v232, v88, v232, v88
	v_fma_f32 v233, v89, v233, v89
	v_fma_f32 v234, v84, v234, v84
	v_fma_f32 v235, v85, v235, v85
	v_mul_f32_e32 v228, 0xbfcc422a, v228
	v_mul_f32_e32 v229, 0xbfcc422a, v229
	v_mul_f32_e32 v230, 0xbfcc422a, v230
	v_mul_f32_e32 v231, 0xbfcc422a, v231
	v_mul_f32_e32 v232, 0xbfcc422a, v232
	v_mul_f32_e32 v233, 0xbfcc422a, v233
	v_mul_f32_e32 v234, 0xbfcc422a, v234
	v_mul_f32_e32 v235, 0xbfcc422a, v235
	v_mul_f32_e32 v228, 0x3fb8aa3b, v228
	v_mul_f32_e32 v229, 0x3fb8aa3b, v229
	v_mul_f32_e32 v230, 0x3fb8aa3b, v230
	v_mul_f32_e32 v231, 0x3fb8aa3b, v231
	v_mul_f32_e32 v232, 0x3fb8aa3b, v232
	v_mul_f32_e32 v233, 0x3fb8aa3b, v233
	v_mul_f32_e32 v234, 0x3fb8aa3b, v234
	v_mul_f32_e32 v235, 0x3fb8aa3b, v235
	v_exp_f32_e32 v228, v228
	v_exp_f32_e32 v229, v229
	v_exp_f32_e32 v230, v230
	v_exp_f32_e32 v231, v231
	v_exp_f32_e32 v232, v232
	v_exp_f32_e32 v233, v233
	v_exp_f32_e32 v234, v234
	v_exp_f32_e32 v235, v235
	v_add_f32_e32 v228, 1.0, v228
	v_add_f32_e32 v229, 1.0, v229
	v_add_f32_e32 v230, 1.0, v230
	v_add_f32_e32 v231, 1.0, v231
	v_add_f32_e32 v232, 1.0, v232
	v_add_f32_e32 v233, 1.0, v233
	v_add_f32_e32 v234, 1.0, v234
	v_add_f32_e32 v235, 1.0, v235
	v_rcp_f32_e32 v228, v228
	v_rcp_f32_e32 v229, v229
	v_rcp_f32_e32 v230, v230
	v_rcp_f32_e32 v231, v231
	v_rcp_f32_e32 v232, v232
	v_rcp_f32_e32 v233, v233
	v_rcp_f32_e32 v234, v234
	v_rcp_f32_e32 v235, v235
	v_pk_mul_f32 v[86:87], v[86:87], v[228:229]
	v_pk_mul_f32 v[82:83], v[82:83], v[230:231]
	v_pk_mul_f32 v[88:89], v[88:89], v[232:233]
	v_pk_mul_f32 v[84:85], v[84:85], v[234:235]
	v_cvt_pk_bf16_f32 v236, v86, v87
	v_cvt_pk_bf16_f32 v237, v88, v89
	v_cvt_pk_bf16_f32 v238, v82, v83
	v_cvt_pk_bf16_f32 v239, v84, v85
	global_store_dwordx4 v[246:247], v[236:239], off
	v_add_co_u32_e32 v152, vcc, 0x40000, v152
	v_addc_co_u32_e32 v153, vcc, 0, v153, vcc
	v_add_co_u32_e32 v246, vcc, 0x40000, v246
	v_addc_co_u32_e32 v247, vcc, 0, v247, vcc
	global_load_dwordx4 v[204:207], v[244:245], off offset:512
	global_load_dwordx4 v[208:211], v[244:245], off offset:528
	v_add_co_u32_e32 v244, vcc, 0x4000, v244
	v_addc_co_u32_e32 v245, vcc, 0, v245, vcc
	s_waitcnt vmcnt(9)
	v_pk_add_f32 v[80:81], v[80:81], v[214:215]
	v_pk_add_f32 v[78:79], v[78:79], v[212:213]
	v_pk_add_f32 v[76:77], v[76:77], v[218:219]
	v_pk_add_f32 v[74:75], v[74:75], v[216:217]
	v_mul_f32_e32 v228, 0x3d372713, v78
	v_mul_f32_e32 v229, 0x3d372713, v79
	v_mul_f32_e32 v230, 0x3d372713, v74
	v_mul_f32_e32 v231, 0x3d372713, v75
	v_mul_f32_e32 v232, 0x3d372713, v80
	v_mul_f32_e32 v233, 0x3d372713, v81
	v_mul_f32_e32 v234, 0x3d372713, v76
	v_mul_f32_e32 v235, 0x3d372713, v77
	v_mul_f32_e32 v228, v78, v228
	v_mul_f32_e32 v229, v79, v229
	v_mul_f32_e32 v230, v74, v230
	v_mul_f32_e32 v231, v75, v231
	v_mul_f32_e32 v232, v80, v232
	v_mul_f32_e32 v233, v81, v233
	v_mul_f32_e32 v234, v76, v234
	v_mul_f32_e32 v235, v77, v235
	v_fma_f32 v228, v78, v228, v78
	v_fma_f32 v229, v79, v229, v79
	v_fma_f32 v230, v74, v230, v74
	v_fma_f32 v231, v75, v231, v75
	v_fma_f32 v232, v80, v232, v80
	v_fma_f32 v233, v81, v233, v81
	v_fma_f32 v234, v76, v234, v76
	v_fma_f32 v235, v77, v235, v77
	v_mul_f32_e32 v228, 0xbfcc422a, v228
	v_mul_f32_e32 v229, 0xbfcc422a, v229
	v_mul_f32_e32 v230, 0xbfcc422a, v230
	v_mul_f32_e32 v231, 0xbfcc422a, v231
	v_mul_f32_e32 v232, 0xbfcc422a, v232
	v_mul_f32_e32 v233, 0xbfcc422a, v233
	v_mul_f32_e32 v234, 0xbfcc422a, v234
	v_mul_f32_e32 v235, 0xbfcc422a, v235
	v_mul_f32_e32 v228, 0x3fb8aa3b, v228
	v_mul_f32_e32 v229, 0x3fb8aa3b, v229
	v_mul_f32_e32 v230, 0x3fb8aa3b, v230
	v_mul_f32_e32 v231, 0x3fb8aa3b, v231
	v_mul_f32_e32 v232, 0x3fb8aa3b, v232
	v_mul_f32_e32 v233, 0x3fb8aa3b, v233
	v_mul_f32_e32 v234, 0x3fb8aa3b, v234
	v_mul_f32_e32 v235, 0x3fb8aa3b, v235
	v_exp_f32_e32 v228, v228
	v_exp_f32_e32 v229, v229
	v_exp_f32_e32 v230, v230
	v_exp_f32_e32 v231, v231
	v_exp_f32_e32 v232, v232
	v_exp_f32_e32 v233, v233
	v_exp_f32_e32 v234, v234
	v_exp_f32_e32 v235, v235
	v_add_f32_e32 v228, 1.0, v228
	v_add_f32_e32 v229, 1.0, v229
	v_add_f32_e32 v230, 1.0, v230
	v_add_f32_e32 v231, 1.0, v231
	v_add_f32_e32 v232, 1.0, v232
	v_add_f32_e32 v233, 1.0, v233
	v_add_f32_e32 v234, 1.0, v234
	v_add_f32_e32 v235, 1.0, v235
	v_rcp_f32_e32 v228, v228
	v_rcp_f32_e32 v229, v229
	v_rcp_f32_e32 v230, v230
	v_rcp_f32_e32 v231, v231
	v_rcp_f32_e32 v232, v232
	v_rcp_f32_e32 v233, v233
	v_rcp_f32_e32 v234, v234
	v_rcp_f32_e32 v235, v235
	v_pk_mul_f32 v[78:79], v[78:79], v[228:229]
	v_pk_mul_f32 v[74:75], v[74:75], v[230:231]
	v_pk_mul_f32 v[80:81], v[80:81], v[232:233]
	v_pk_mul_f32 v[76:77], v[76:77], v[234:235]
	v_cvt_pk_bf16_f32 v236, v78, v79
	v_cvt_pk_bf16_f32 v237, v80, v81
	v_cvt_pk_bf16_f32 v238, v74, v75
	v_cvt_pk_bf16_f32 v239, v76, v77
	global_store_dwordx4 v[152:153], v[236:239], off
	global_load_dwordx4 v[212:215], v[244:245], off
	global_load_dwordx4 v[216:219], v[244:245], off offset:16
	s_waitcnt vmcnt(9)
	v_pk_add_f32 v[72:73], v[72:73], v[222:223]
	v_pk_add_f32 v[70:71], v[70:71], v[220:221]
	v_pk_add_f32 v[68:69], v[68:69], v[226:227]
	v_pk_add_f32 v[66:67], v[66:67], v[224:225]
	v_mul_f32_e32 v228, 0x3d372713, v70
	v_mul_f32_e32 v229, 0x3d372713, v71
	v_mul_f32_e32 v230, 0x3d372713, v66
	v_mul_f32_e32 v231, 0x3d372713, v67
	v_mul_f32_e32 v232, 0x3d372713, v72
	v_mul_f32_e32 v233, 0x3d372713, v73
	v_mul_f32_e32 v234, 0x3d372713, v68
	v_mul_f32_e32 v235, 0x3d372713, v69
	v_mul_f32_e32 v228, v70, v228
	v_mul_f32_e32 v229, v71, v229
	v_mul_f32_e32 v230, v66, v230
	v_mul_f32_e32 v231, v67, v231
	v_mul_f32_e32 v232, v72, v232
	v_mul_f32_e32 v233, v73, v233
	v_mul_f32_e32 v234, v68, v234
	v_mul_f32_e32 v235, v69, v235
	v_fma_f32 v228, v70, v228, v70
	v_fma_f32 v229, v71, v229, v71
	v_fma_f32 v230, v66, v230, v66
	v_fma_f32 v231, v67, v231, v67
	v_fma_f32 v232, v72, v232, v72
	v_fma_f32 v233, v73, v233, v73
	v_fma_f32 v234, v68, v234, v68
	v_fma_f32 v235, v69, v235, v69
	v_mul_f32_e32 v228, 0xbfcc422a, v228
	v_mul_f32_e32 v229, 0xbfcc422a, v229
	v_mul_f32_e32 v230, 0xbfcc422a, v230
	v_mul_f32_e32 v231, 0xbfcc422a, v231
	v_mul_f32_e32 v232, 0xbfcc422a, v232
	v_mul_f32_e32 v233, 0xbfcc422a, v233
	v_mul_f32_e32 v234, 0xbfcc422a, v234
	v_mul_f32_e32 v235, 0xbfcc422a, v235
	v_mul_f32_e32 v228, 0x3fb8aa3b, v228
	v_mul_f32_e32 v229, 0x3fb8aa3b, v229
	v_mul_f32_e32 v230, 0x3fb8aa3b, v230
	v_mul_f32_e32 v231, 0x3fb8aa3b, v231
	v_mul_f32_e32 v232, 0x3fb8aa3b, v232
	v_mul_f32_e32 v233, 0x3fb8aa3b, v233
	v_mul_f32_e32 v234, 0x3fb8aa3b, v234
	v_mul_f32_e32 v235, 0x3fb8aa3b, v235
	v_exp_f32_e32 v228, v228
	v_exp_f32_e32 v229, v229
	v_exp_f32_e32 v230, v230
	v_exp_f32_e32 v231, v231
	v_exp_f32_e32 v232, v232
	v_exp_f32_e32 v233, v233
	v_exp_f32_e32 v234, v234
	v_exp_f32_e32 v235, v235
	v_add_f32_e32 v228, 1.0, v228
	v_add_f32_e32 v229, 1.0, v229
	v_add_f32_e32 v230, 1.0, v230
	v_add_f32_e32 v231, 1.0, v231
	v_add_f32_e32 v232, 1.0, v232
	v_add_f32_e32 v233, 1.0, v233
	v_add_f32_e32 v234, 1.0, v234
	v_add_f32_e32 v235, 1.0, v235
	v_rcp_f32_e32 v228, v228
	v_rcp_f32_e32 v229, v229
	v_rcp_f32_e32 v230, v230
	v_rcp_f32_e32 v231, v231
	v_rcp_f32_e32 v232, v232
	v_rcp_f32_e32 v233, v233
	v_rcp_f32_e32 v234, v234
	v_rcp_f32_e32 v235, v235
	v_pk_mul_f32 v[70:71], v[70:71], v[228:229]
	v_pk_mul_f32 v[66:67], v[66:67], v[230:231]
	v_pk_mul_f32 v[72:73], v[72:73], v[232:233]
	v_pk_mul_f32 v[68:69], v[68:69], v[234:235]
	v_cvt_pk_bf16_f32 v236, v70, v71
	v_cvt_pk_bf16_f32 v237, v72, v73
	v_cvt_pk_bf16_f32 v238, v66, v67
	v_cvt_pk_bf16_f32 v239, v68, v69
	global_store_dwordx4 v[246:247], v[236:239], off
	v_add_co_u32_e32 v152, vcc, 0x140000, v152
	v_addc_co_u32_e32 v153, vcc, 0, v153, vcc
	v_add_co_u32_e32 v246, vcc, 0x140000, v246
	v_addc_co_u32_e32 v247, vcc, 0, v247, vcc
	global_load_dwordx4 v[220:223], v[244:245], off offset:512
	global_load_dwordx4 v[224:227], v[244:245], off offset:528
	v_add_co_u32_e32 v244, vcc, 0x4000, v244
	v_addc_co_u32_e32 v245, vcc, 0, v245, vcc
	s_waitcnt vmcnt(9)
	v_pk_add_f32 v[64:65], v[64:65], v[198:199]
	v_pk_add_f32 v[62:63], v[62:63], v[196:197]
	v_pk_add_f32 v[60:61], v[60:61], v[202:203]
	v_pk_add_f32 v[58:59], v[58:59], v[200:201]
	v_mul_f32_e32 v228, 0x3d372713, v62
	v_mul_f32_e32 v229, 0x3d372713, v63
	v_mul_f32_e32 v230, 0x3d372713, v58
	v_mul_f32_e32 v231, 0x3d372713, v59
	v_mul_f32_e32 v232, 0x3d372713, v64
	v_mul_f32_e32 v233, 0x3d372713, v65
	v_mul_f32_e32 v234, 0x3d372713, v60
	v_mul_f32_e32 v235, 0x3d372713, v61
	v_mul_f32_e32 v228, v62, v228
	v_mul_f32_e32 v229, v63, v229
	v_mul_f32_e32 v230, v58, v230
	v_mul_f32_e32 v231, v59, v231
	v_mul_f32_e32 v232, v64, v232
	v_mul_f32_e32 v233, v65, v233
	v_mul_f32_e32 v234, v60, v234
	v_mul_f32_e32 v235, v61, v235
	v_fma_f32 v228, v62, v228, v62
	v_fma_f32 v229, v63, v229, v63
	v_fma_f32 v230, v58, v230, v58
	v_fma_f32 v231, v59, v231, v59
	v_fma_f32 v232, v64, v232, v64
	v_fma_f32 v233, v65, v233, v65
	v_fma_f32 v234, v60, v234, v60
	v_fma_f32 v235, v61, v235, v61
	v_mul_f32_e32 v228, 0xbfcc422a, v228
	v_mul_f32_e32 v229, 0xbfcc422a, v229
	v_mul_f32_e32 v230, 0xbfcc422a, v230
	v_mul_f32_e32 v231, 0xbfcc422a, v231
	v_mul_f32_e32 v232, 0xbfcc422a, v232
	v_mul_f32_e32 v233, 0xbfcc422a, v233
	v_mul_f32_e32 v234, 0xbfcc422a, v234
	v_mul_f32_e32 v235, 0xbfcc422a, v235
	v_mul_f32_e32 v228, 0x3fb8aa3b, v228
	v_mul_f32_e32 v229, 0x3fb8aa3b, v229
	v_mul_f32_e32 v230, 0x3fb8aa3b, v230
	v_mul_f32_e32 v231, 0x3fb8aa3b, v231
	v_mul_f32_e32 v232, 0x3fb8aa3b, v232
	v_mul_f32_e32 v233, 0x3fb8aa3b, v233
	v_mul_f32_e32 v234, 0x3fb8aa3b, v234
	v_mul_f32_e32 v235, 0x3fb8aa3b, v235
	v_exp_f32_e32 v228, v228
	v_exp_f32_e32 v229, v229
	v_exp_f32_e32 v230, v230
	v_exp_f32_e32 v231, v231
	v_exp_f32_e32 v232, v232
	v_exp_f32_e32 v233, v233
	v_exp_f32_e32 v234, v234
	v_exp_f32_e32 v235, v235
	v_add_f32_e32 v228, 1.0, v228
	v_add_f32_e32 v229, 1.0, v229
	v_add_f32_e32 v230, 1.0, v230
	v_add_f32_e32 v231, 1.0, v231
	v_add_f32_e32 v232, 1.0, v232
	v_add_f32_e32 v233, 1.0, v233
	v_add_f32_e32 v234, 1.0, v234
	v_add_f32_e32 v235, 1.0, v235
	v_rcp_f32_e32 v228, v228
	v_rcp_f32_e32 v229, v229
	v_rcp_f32_e32 v230, v230
	v_rcp_f32_e32 v231, v231
	v_rcp_f32_e32 v232, v232
	v_rcp_f32_e32 v233, v233
	v_rcp_f32_e32 v234, v234
	v_rcp_f32_e32 v235, v235
	v_pk_mul_f32 v[62:63], v[62:63], v[228:229]
	v_pk_mul_f32 v[58:59], v[58:59], v[230:231]
	v_pk_mul_f32 v[64:65], v[64:65], v[232:233]
	v_pk_mul_f32 v[60:61], v[60:61], v[234:235]
	v_cvt_pk_bf16_f32 v236, v62, v63
	v_cvt_pk_bf16_f32 v237, v64, v65
	v_cvt_pk_bf16_f32 v238, v58, v59
	v_cvt_pk_bf16_f32 v239, v60, v61
	global_store_dwordx4 v[152:153], v[236:239], off
	global_load_dwordx4 v[196:199], v[244:245], off
	global_load_dwordx4 v[200:203], v[244:245], off offset:16
	s_waitcnt vmcnt(9)
	v_pk_add_f32 v[56:57], v[56:57], v[206:207]
	v_pk_add_f32 v[54:55], v[54:55], v[204:205]
	v_pk_add_f32 v[52:53], v[52:53], v[210:211]
	v_pk_add_f32 v[50:51], v[50:51], v[208:209]
	v_mul_f32_e32 v228, 0x3d372713, v54
	v_mul_f32_e32 v229, 0x3d372713, v55
	v_mul_f32_e32 v230, 0x3d372713, v50
	v_mul_f32_e32 v231, 0x3d372713, v51
	v_mul_f32_e32 v232, 0x3d372713, v56
	v_mul_f32_e32 v233, 0x3d372713, v57
	v_mul_f32_e32 v234, 0x3d372713, v52
	v_mul_f32_e32 v235, 0x3d372713, v53
	v_mul_f32_e32 v228, v54, v228
	v_mul_f32_e32 v229, v55, v229
	v_mul_f32_e32 v230, v50, v230
	v_mul_f32_e32 v231, v51, v231
	v_mul_f32_e32 v232, v56, v232
	v_mul_f32_e32 v233, v57, v233
	v_mul_f32_e32 v234, v52, v234
	v_mul_f32_e32 v235, v53, v235
	v_fma_f32 v228, v54, v228, v54
	v_fma_f32 v229, v55, v229, v55
	v_fma_f32 v230, v50, v230, v50
	v_fma_f32 v231, v51, v231, v51
	v_fma_f32 v232, v56, v232, v56
	v_fma_f32 v233, v57, v233, v57
	v_fma_f32 v234, v52, v234, v52
	v_fma_f32 v235, v53, v235, v53
	v_mul_f32_e32 v228, 0xbfcc422a, v228
	v_mul_f32_e32 v229, 0xbfcc422a, v229
	v_mul_f32_e32 v230, 0xbfcc422a, v230
	v_mul_f32_e32 v231, 0xbfcc422a, v231
	v_mul_f32_e32 v232, 0xbfcc422a, v232
	v_mul_f32_e32 v233, 0xbfcc422a, v233
	v_mul_f32_e32 v234, 0xbfcc422a, v234
	v_mul_f32_e32 v235, 0xbfcc422a, v235
	v_mul_f32_e32 v228, 0x3fb8aa3b, v228
	v_mul_f32_e32 v229, 0x3fb8aa3b, v229
	v_mul_f32_e32 v230, 0x3fb8aa3b, v230
	v_mul_f32_e32 v231, 0x3fb8aa3b, v231
	v_mul_f32_e32 v232, 0x3fb8aa3b, v232
	v_mul_f32_e32 v233, 0x3fb8aa3b, v233
	v_mul_f32_e32 v234, 0x3fb8aa3b, v234
	v_mul_f32_e32 v235, 0x3fb8aa3b, v235
	v_exp_f32_e32 v228, v228
	v_exp_f32_e32 v229, v229
	v_exp_f32_e32 v230, v230
	v_exp_f32_e32 v231, v231
	v_exp_f32_e32 v232, v232
	v_exp_f32_e32 v233, v233
	v_exp_f32_e32 v234, v234
	v_exp_f32_e32 v235, v235
	v_add_f32_e32 v228, 1.0, v228
	v_add_f32_e32 v229, 1.0, v229
	v_add_f32_e32 v230, 1.0, v230
	v_add_f32_e32 v231, 1.0, v231
	v_add_f32_e32 v232, 1.0, v232
	v_add_f32_e32 v233, 1.0, v233
	v_add_f32_e32 v234, 1.0, v234
	v_add_f32_e32 v235, 1.0, v235
	v_rcp_f32_e32 v228, v228
	v_rcp_f32_e32 v229, v229
	v_rcp_f32_e32 v230, v230
	v_rcp_f32_e32 v231, v231
	v_rcp_f32_e32 v232, v232
	v_rcp_f32_e32 v233, v233
	v_rcp_f32_e32 v234, v234
	v_rcp_f32_e32 v235, v235
	v_pk_mul_f32 v[54:55], v[54:55], v[228:229]
	v_pk_mul_f32 v[50:51], v[50:51], v[230:231]
	v_pk_mul_f32 v[56:57], v[56:57], v[232:233]
	v_pk_mul_f32 v[52:53], v[52:53], v[234:235]
	v_cvt_pk_bf16_f32 v236, v54, v55
	v_cvt_pk_bf16_f32 v237, v56, v57
	v_cvt_pk_bf16_f32 v238, v50, v51
	v_cvt_pk_bf16_f32 v239, v52, v53
	global_store_dwordx4 v[246:247], v[236:239], off
	v_add_co_u32_e32 v152, vcc, 0x40000, v152
	v_addc_co_u32_e32 v153, vcc, 0, v153, vcc
	v_add_co_u32_e32 v246, vcc, 0x40000, v246
	v_addc_co_u32_e32 v247, vcc, 0, v247, vcc
	global_load_dwordx4 v[204:207], v[244:245], off offset:512
	global_load_dwordx4 v[208:211], v[244:245], off offset:528
	v_add_co_u32_e32 v244, vcc, 0x4000, v244
	v_addc_co_u32_e32 v245, vcc, 0, v245, vcc
	s_waitcnt vmcnt(9)
	v_pk_add_f32 v[48:49], v[48:49], v[214:215]
	v_pk_add_f32 v[46:47], v[46:47], v[212:213]
	v_pk_add_f32 v[44:45], v[44:45], v[218:219]
	v_pk_add_f32 v[42:43], v[42:43], v[216:217]
	v_mul_f32_e32 v228, 0x3d372713, v46
	v_mul_f32_e32 v229, 0x3d372713, v47
	v_mul_f32_e32 v230, 0x3d372713, v42
	v_mul_f32_e32 v231, 0x3d372713, v43
	v_mul_f32_e32 v232, 0x3d372713, v48
	v_mul_f32_e32 v233, 0x3d372713, v49
	v_mul_f32_e32 v234, 0x3d372713, v44
	v_mul_f32_e32 v235, 0x3d372713, v45
	v_mul_f32_e32 v228, v46, v228
	v_mul_f32_e32 v229, v47, v229
	v_mul_f32_e32 v230, v42, v230
	v_mul_f32_e32 v231, v43, v231
	v_mul_f32_e32 v232, v48, v232
	v_mul_f32_e32 v233, v49, v233
	v_mul_f32_e32 v234, v44, v234
	v_mul_f32_e32 v235, v45, v235
	v_fma_f32 v228, v46, v228, v46
	v_fma_f32 v229, v47, v229, v47
	v_fma_f32 v230, v42, v230, v42
	v_fma_f32 v231, v43, v231, v43
	v_fma_f32 v232, v48, v232, v48
	v_fma_f32 v233, v49, v233, v49
	v_fma_f32 v234, v44, v234, v44
	v_fma_f32 v235, v45, v235, v45
	v_mul_f32_e32 v228, 0xbfcc422a, v228
	v_mul_f32_e32 v229, 0xbfcc422a, v229
	v_mul_f32_e32 v230, 0xbfcc422a, v230
	v_mul_f32_e32 v231, 0xbfcc422a, v231
	v_mul_f32_e32 v232, 0xbfcc422a, v232
	v_mul_f32_e32 v233, 0xbfcc422a, v233
	v_mul_f32_e32 v234, 0xbfcc422a, v234
	v_mul_f32_e32 v235, 0xbfcc422a, v235
	v_mul_f32_e32 v228, 0x3fb8aa3b, v228
	v_mul_f32_e32 v229, 0x3fb8aa3b, v229
	v_mul_f32_e32 v230, 0x3fb8aa3b, v230
	v_mul_f32_e32 v231, 0x3fb8aa3b, v231
	v_mul_f32_e32 v232, 0x3fb8aa3b, v232
	v_mul_f32_e32 v233, 0x3fb8aa3b, v233
	v_mul_f32_e32 v234, 0x3fb8aa3b, v234
	v_mul_f32_e32 v235, 0x3fb8aa3b, v235
	v_exp_f32_e32 v228, v228
	v_exp_f32_e32 v229, v229
	v_exp_f32_e32 v230, v230
	v_exp_f32_e32 v231, v231
	v_exp_f32_e32 v232, v232
	v_exp_f32_e32 v233, v233
	v_exp_f32_e32 v234, v234
	v_exp_f32_e32 v235, v235
	v_add_f32_e32 v228, 1.0, v228
	v_add_f32_e32 v229, 1.0, v229
	v_add_f32_e32 v230, 1.0, v230
	v_add_f32_e32 v231, 1.0, v231
	v_add_f32_e32 v232, 1.0, v232
	v_add_f32_e32 v233, 1.0, v233
	v_add_f32_e32 v234, 1.0, v234
	v_add_f32_e32 v235, 1.0, v235
	v_rcp_f32_e32 v228, v228
	v_rcp_f32_e32 v229, v229
	v_rcp_f32_e32 v230, v230
	v_rcp_f32_e32 v231, v231
	v_rcp_f32_e32 v232, v232
	v_rcp_f32_e32 v233, v233
	v_rcp_f32_e32 v234, v234
	v_rcp_f32_e32 v235, v235
	v_pk_mul_f32 v[46:47], v[46:47], v[228:229]
	v_pk_mul_f32 v[42:43], v[42:43], v[230:231]
	v_pk_mul_f32 v[48:49], v[48:49], v[232:233]
	v_pk_mul_f32 v[44:45], v[44:45], v[234:235]
	v_cvt_pk_bf16_f32 v236, v46, v47
	v_cvt_pk_bf16_f32 v237, v48, v49
	v_cvt_pk_bf16_f32 v238, v42, v43
	v_cvt_pk_bf16_f32 v239, v44, v45
	global_store_dwordx4 v[152:153], v[236:239], off
	global_load_dwordx4 v[212:215], v[244:245], off
	global_load_dwordx4 v[216:219], v[244:245], off offset:16
	s_waitcnt vmcnt(9)
	v_pk_add_f32 v[40:41], v[40:41], v[222:223]
	v_pk_add_f32 v[38:39], v[38:39], v[220:221]
	v_pk_add_f32 v[36:37], v[36:37], v[226:227]
	v_pk_add_f32 v[34:35], v[34:35], v[224:225]
	v_mul_f32_e32 v228, 0x3d372713, v38
	v_mul_f32_e32 v229, 0x3d372713, v39
	v_mul_f32_e32 v230, 0x3d372713, v34
	v_mul_f32_e32 v231, 0x3d372713, v35
	v_mul_f32_e32 v232, 0x3d372713, v40
	v_mul_f32_e32 v233, 0x3d372713, v41
	v_mul_f32_e32 v234, 0x3d372713, v36
	v_mul_f32_e32 v235, 0x3d372713, v37
	v_mul_f32_e32 v228, v38, v228
	v_mul_f32_e32 v229, v39, v229
	v_mul_f32_e32 v230, v34, v230
	v_mul_f32_e32 v231, v35, v231
	v_mul_f32_e32 v232, v40, v232
	v_mul_f32_e32 v233, v41, v233
	v_mul_f32_e32 v234, v36, v234
	v_mul_f32_e32 v235, v37, v235
	v_fma_f32 v228, v38, v228, v38
	v_fma_f32 v229, v39, v229, v39
	v_fma_f32 v230, v34, v230, v34
	v_fma_f32 v231, v35, v231, v35
	v_fma_f32 v232, v40, v232, v40
	v_fma_f32 v233, v41, v233, v41
	v_fma_f32 v234, v36, v234, v36
	v_fma_f32 v235, v37, v235, v37
	v_mul_f32_e32 v228, 0xbfcc422a, v228
	v_mul_f32_e32 v229, 0xbfcc422a, v229
	v_mul_f32_e32 v230, 0xbfcc422a, v230
	v_mul_f32_e32 v231, 0xbfcc422a, v231
	v_mul_f32_e32 v232, 0xbfcc422a, v232
	v_mul_f32_e32 v233, 0xbfcc422a, v233
	v_mul_f32_e32 v234, 0xbfcc422a, v234
	v_mul_f32_e32 v235, 0xbfcc422a, v235
	v_mul_f32_e32 v228, 0x3fb8aa3b, v228
	v_mul_f32_e32 v229, 0x3fb8aa3b, v229
	v_mul_f32_e32 v230, 0x3fb8aa3b, v230
	v_mul_f32_e32 v231, 0x3fb8aa3b, v231
	v_mul_f32_e32 v232, 0x3fb8aa3b, v232
	v_mul_f32_e32 v233, 0x3fb8aa3b, v233
	v_mul_f32_e32 v234, 0x3fb8aa3b, v234
	v_mul_f32_e32 v235, 0x3fb8aa3b, v235
	v_exp_f32_e32 v228, v228
	v_exp_f32_e32 v229, v229
	v_exp_f32_e32 v230, v230
	v_exp_f32_e32 v231, v231
	v_exp_f32_e32 v232, v232
	v_exp_f32_e32 v233, v233
	v_exp_f32_e32 v234, v234
	v_exp_f32_e32 v235, v235
	v_add_f32_e32 v228, 1.0, v228
	v_add_f32_e32 v229, 1.0, v229
	v_add_f32_e32 v230, 1.0, v230
	v_add_f32_e32 v231, 1.0, v231
	v_add_f32_e32 v232, 1.0, v232
	v_add_f32_e32 v233, 1.0, v233
	v_add_f32_e32 v234, 1.0, v234
	v_add_f32_e32 v235, 1.0, v235
	v_rcp_f32_e32 v228, v228
	v_rcp_f32_e32 v229, v229
	v_rcp_f32_e32 v230, v230
	v_rcp_f32_e32 v231, v231
	v_rcp_f32_e32 v232, v232
	v_rcp_f32_e32 v233, v233
	v_rcp_f32_e32 v234, v234
	v_rcp_f32_e32 v235, v235
	v_pk_mul_f32 v[38:39], v[38:39], v[228:229]
	v_pk_mul_f32 v[34:35], v[34:35], v[230:231]
	v_pk_mul_f32 v[40:41], v[40:41], v[232:233]
	v_pk_mul_f32 v[36:37], v[36:37], v[234:235]
	v_cvt_pk_bf16_f32 v236, v38, v39
	v_cvt_pk_bf16_f32 v237, v40, v41
	v_cvt_pk_bf16_f32 v238, v34, v35
	v_cvt_pk_bf16_f32 v239, v36, v37
	global_store_dwordx4 v[246:247], v[236:239], off
	v_add_co_u32_e32 v152, vcc, 0x40000, v152
	v_addc_co_u32_e32 v153, vcc, 0, v153, vcc
	v_add_co_u32_e32 v246, vcc, 0x40000, v246
	v_addc_co_u32_e32 v247, vcc, 0, v247, vcc
	global_load_dwordx4 v[220:223], v[244:245], off offset:512
	global_load_dwordx4 v[224:227], v[244:245], off offset:528
	s_waitcnt vmcnt(9)
	v_pk_add_f32 v[32:33], v[32:33], v[198:199]
	v_pk_add_f32 v[30:31], v[30:31], v[196:197]
	v_pk_add_f32 v[28:29], v[28:29], v[202:203]
	v_pk_add_f32 v[26:27], v[26:27], v[200:201]
	v_mul_f32_e32 v228, 0x3d372713, v30
	v_mul_f32_e32 v229, 0x3d372713, v31
	v_mul_f32_e32 v230, 0x3d372713, v26
	v_mul_f32_e32 v231, 0x3d372713, v27
	v_mul_f32_e32 v232, 0x3d372713, v32
	v_mul_f32_e32 v233, 0x3d372713, v33
	v_mul_f32_e32 v234, 0x3d372713, v28
	v_mul_f32_e32 v235, 0x3d372713, v29
	v_mul_f32_e32 v228, v30, v228
	v_mul_f32_e32 v229, v31, v229
	v_mul_f32_e32 v230, v26, v230
	v_mul_f32_e32 v231, v27, v231
	v_mul_f32_e32 v232, v32, v232
	v_mul_f32_e32 v233, v33, v233
	v_mul_f32_e32 v234, v28, v234
	v_mul_f32_e32 v235, v29, v235
	v_fma_f32 v228, v30, v228, v30
	v_fma_f32 v229, v31, v229, v31
	v_fma_f32 v230, v26, v230, v26
	v_fma_f32 v231, v27, v231, v27
	v_fma_f32 v232, v32, v232, v32
	v_fma_f32 v233, v33, v233, v33
	v_fma_f32 v234, v28, v234, v28
	v_fma_f32 v235, v29, v235, v29
	v_mul_f32_e32 v228, 0xbfcc422a, v228
	v_mul_f32_e32 v229, 0xbfcc422a, v229
	v_mul_f32_e32 v230, 0xbfcc422a, v230
	v_mul_f32_e32 v231, 0xbfcc422a, v231
	v_mul_f32_e32 v232, 0xbfcc422a, v232
	v_mul_f32_e32 v233, 0xbfcc422a, v233
	v_mul_f32_e32 v234, 0xbfcc422a, v234
	v_mul_f32_e32 v235, 0xbfcc422a, v235
	v_mul_f32_e32 v228, 0x3fb8aa3b, v228
	v_mul_f32_e32 v229, 0x3fb8aa3b, v229
	v_mul_f32_e32 v230, 0x3fb8aa3b, v230
	v_mul_f32_e32 v231, 0x3fb8aa3b, v231
	v_mul_f32_e32 v232, 0x3fb8aa3b, v232
	v_mul_f32_e32 v233, 0x3fb8aa3b, v233
	v_mul_f32_e32 v234, 0x3fb8aa3b, v234
	v_mul_f32_e32 v235, 0x3fb8aa3b, v235
	v_exp_f32_e32 v228, v228
	v_exp_f32_e32 v229, v229
	v_exp_f32_e32 v230, v230
	v_exp_f32_e32 v231, v231
	v_exp_f32_e32 v232, v232
	v_exp_f32_e32 v233, v233
	v_exp_f32_e32 v234, v234
	v_exp_f32_e32 v235, v235
	v_add_f32_e32 v228, 1.0, v228
	v_add_f32_e32 v229, 1.0, v229
	v_add_f32_e32 v230, 1.0, v230
	v_add_f32_e32 v231, 1.0, v231
	v_add_f32_e32 v232, 1.0, v232
	v_add_f32_e32 v233, 1.0, v233
	v_add_f32_e32 v234, 1.0, v234
	v_add_f32_e32 v235, 1.0, v235
	v_rcp_f32_e32 v228, v228
	v_rcp_f32_e32 v229, v229
	v_rcp_f32_e32 v230, v230
	v_rcp_f32_e32 v231, v231
	v_rcp_f32_e32 v232, v232
	v_rcp_f32_e32 v233, v233
	v_rcp_f32_e32 v234, v234
	v_rcp_f32_e32 v235, v235
	v_pk_mul_f32 v[30:31], v[30:31], v[228:229]
	v_pk_mul_f32 v[26:27], v[26:27], v[230:231]
	v_pk_mul_f32 v[32:33], v[32:33], v[232:233]
	v_pk_mul_f32 v[28:29], v[28:29], v[234:235]
	v_cvt_pk_bf16_f32 v236, v30, v31
	v_cvt_pk_bf16_f32 v237, v32, v33
	v_cvt_pk_bf16_f32 v238, v26, v27
	v_cvt_pk_bf16_f32 v239, v28, v29
	global_store_dwordx4 v[152:153], v[236:239], off
	s_waitcnt vmcnt(7)
	v_pk_add_f32 v[24:25], v[24:25], v[206:207]
	v_pk_add_f32 v[22:23], v[22:23], v[204:205]
	v_pk_add_f32 v[20:21], v[20:21], v[210:211]
	v_pk_add_f32 v[18:19], v[18:19], v[208:209]
	v_mul_f32_e32 v228, 0x3d372713, v22
	v_mul_f32_e32 v229, 0x3d372713, v23
	v_mul_f32_e32 v230, 0x3d372713, v18
	v_mul_f32_e32 v231, 0x3d372713, v19
	v_mul_f32_e32 v232, 0x3d372713, v24
	v_mul_f32_e32 v233, 0x3d372713, v25
	v_mul_f32_e32 v234, 0x3d372713, v20
	v_mul_f32_e32 v235, 0x3d372713, v21
	v_mul_f32_e32 v228, v22, v228
	v_mul_f32_e32 v229, v23, v229
	v_mul_f32_e32 v230, v18, v230
	v_mul_f32_e32 v231, v19, v231
	v_mul_f32_e32 v232, v24, v232
	v_mul_f32_e32 v233, v25, v233
	v_mul_f32_e32 v234, v20, v234
	v_mul_f32_e32 v235, v21, v235
	v_fma_f32 v228, v22, v228, v22
	v_fma_f32 v229, v23, v229, v23
	v_fma_f32 v230, v18, v230, v18
	v_fma_f32 v231, v19, v231, v19
	v_fma_f32 v232, v24, v232, v24
	v_fma_f32 v233, v25, v233, v25
	v_fma_f32 v234, v20, v234, v20
	v_fma_f32 v235, v21, v235, v21
	v_mul_f32_e32 v228, 0xbfcc422a, v228
	v_mul_f32_e32 v229, 0xbfcc422a, v229
	v_mul_f32_e32 v230, 0xbfcc422a, v230
	v_mul_f32_e32 v231, 0xbfcc422a, v231
	v_mul_f32_e32 v232, 0xbfcc422a, v232
	v_mul_f32_e32 v233, 0xbfcc422a, v233
	v_mul_f32_e32 v234, 0xbfcc422a, v234
	v_mul_f32_e32 v235, 0xbfcc422a, v235
	v_mul_f32_e32 v228, 0x3fb8aa3b, v228
	v_mul_f32_e32 v229, 0x3fb8aa3b, v229
	v_mul_f32_e32 v230, 0x3fb8aa3b, v230
	v_mul_f32_e32 v231, 0x3fb8aa3b, v231
	v_mul_f32_e32 v232, 0x3fb8aa3b, v232
	v_mul_f32_e32 v233, 0x3fb8aa3b, v233
	v_mul_f32_e32 v234, 0x3fb8aa3b, v234
	v_mul_f32_e32 v235, 0x3fb8aa3b, v235
	v_exp_f32_e32 v228, v228
	v_exp_f32_e32 v229, v229
	v_exp_f32_e32 v230, v230
	v_exp_f32_e32 v231, v231
	v_exp_f32_e32 v232, v232
	v_exp_f32_e32 v233, v233
	v_exp_f32_e32 v234, v234
	v_exp_f32_e32 v235, v235
	v_add_f32_e32 v228, 1.0, v228
	v_add_f32_e32 v229, 1.0, v229
	v_add_f32_e32 v230, 1.0, v230
	v_add_f32_e32 v231, 1.0, v231
	v_add_f32_e32 v232, 1.0, v232
	v_add_f32_e32 v233, 1.0, v233
	v_add_f32_e32 v234, 1.0, v234
	v_add_f32_e32 v235, 1.0, v235
	v_rcp_f32_e32 v228, v228
	v_rcp_f32_e32 v229, v229
	v_rcp_f32_e32 v230, v230
	v_rcp_f32_e32 v231, v231
	v_rcp_f32_e32 v232, v232
	v_rcp_f32_e32 v233, v233
	v_rcp_f32_e32 v234, v234
	v_rcp_f32_e32 v235, v235
	v_pk_mul_f32 v[22:23], v[22:23], v[228:229]
	v_pk_mul_f32 v[18:19], v[18:19], v[230:231]
	v_pk_mul_f32 v[24:25], v[24:25], v[232:233]
	v_pk_mul_f32 v[20:21], v[20:21], v[234:235]
	v_cvt_pk_bf16_f32 v236, v22, v23
	v_cvt_pk_bf16_f32 v237, v24, v25
	v_cvt_pk_bf16_f32 v238, v18, v19
	v_cvt_pk_bf16_f32 v239, v20, v21
	global_store_dwordx4 v[246:247], v[236:239], off
	v_add_co_u32_e32 v152, vcc, 0x40000, v152
	v_addc_co_u32_e32 v153, vcc, 0, v153, vcc
	v_add_co_u32_e32 v246, vcc, 0x40000, v246
	v_addc_co_u32_e32 v247, vcc, 0, v247, vcc
	s_waitcnt vmcnt(5)
	v_pk_add_f32 v[16:17], v[16:17], v[214:215]
	v_pk_add_f32 v[14:15], v[14:15], v[212:213]
	v_pk_add_f32 v[12:13], v[12:13], v[218:219]
	v_pk_add_f32 v[10:11], v[10:11], v[216:217]
	v_mul_f32_e32 v228, 0x3d372713, v14
	v_mul_f32_e32 v229, 0x3d372713, v15
	v_mul_f32_e32 v230, 0x3d372713, v10
	v_mul_f32_e32 v231, 0x3d372713, v11
	v_mul_f32_e32 v232, 0x3d372713, v16
	v_mul_f32_e32 v233, 0x3d372713, v17
	v_mul_f32_e32 v234, 0x3d372713, v12
	v_mul_f32_e32 v235, 0x3d372713, v13
	v_mul_f32_e32 v228, v14, v228
	v_mul_f32_e32 v229, v15, v229
	v_mul_f32_e32 v230, v10, v230
	v_mul_f32_e32 v231, v11, v231
	v_mul_f32_e32 v232, v16, v232
	v_mul_f32_e32 v233, v17, v233
	v_mul_f32_e32 v234, v12, v234
	v_mul_f32_e32 v235, v13, v235
	v_fma_f32 v228, v14, v228, v14
	v_fma_f32 v229, v15, v229, v15
	v_fma_f32 v230, v10, v230, v10
	v_fma_f32 v231, v11, v231, v11
	v_fma_f32 v232, v16, v232, v16
	v_fma_f32 v233, v17, v233, v17
	v_fma_f32 v234, v12, v234, v12
	v_fma_f32 v235, v13, v235, v13
	v_mul_f32_e32 v228, 0xbfcc422a, v228
	v_mul_f32_e32 v229, 0xbfcc422a, v229
	v_mul_f32_e32 v230, 0xbfcc422a, v230
	v_mul_f32_e32 v231, 0xbfcc422a, v231
	v_mul_f32_e32 v232, 0xbfcc422a, v232
	v_mul_f32_e32 v233, 0xbfcc422a, v233
	v_mul_f32_e32 v234, 0xbfcc422a, v234
	v_mul_f32_e32 v235, 0xbfcc422a, v235
	v_mul_f32_e32 v228, 0x3fb8aa3b, v228
	v_mul_f32_e32 v229, 0x3fb8aa3b, v229
	v_mul_f32_e32 v230, 0x3fb8aa3b, v230
	v_mul_f32_e32 v231, 0x3fb8aa3b, v231
	v_mul_f32_e32 v232, 0x3fb8aa3b, v232
	v_mul_f32_e32 v233, 0x3fb8aa3b, v233
	v_mul_f32_e32 v234, 0x3fb8aa3b, v234
	v_mul_f32_e32 v235, 0x3fb8aa3b, v235
	v_exp_f32_e32 v228, v228
	v_exp_f32_e32 v229, v229
	v_exp_f32_e32 v230, v230
	v_exp_f32_e32 v231, v231
	v_exp_f32_e32 v232, v232
	v_exp_f32_e32 v233, v233
	v_exp_f32_e32 v234, v234
	v_exp_f32_e32 v235, v235
	v_add_f32_e32 v228, 1.0, v228
	v_add_f32_e32 v229, 1.0, v229
	v_add_f32_e32 v230, 1.0, v230
	v_add_f32_e32 v231, 1.0, v231
	v_add_f32_e32 v232, 1.0, v232
	v_add_f32_e32 v233, 1.0, v233
	v_add_f32_e32 v234, 1.0, v234
	v_add_f32_e32 v235, 1.0, v235
	v_rcp_f32_e32 v228, v228
	v_rcp_f32_e32 v229, v229
	v_rcp_f32_e32 v230, v230
	v_rcp_f32_e32 v231, v231
	v_rcp_f32_e32 v232, v232
	v_rcp_f32_e32 v233, v233
	v_rcp_f32_e32 v234, v234
	v_rcp_f32_e32 v235, v235
	v_pk_mul_f32 v[14:15], v[14:15], v[228:229]
	v_pk_mul_f32 v[10:11], v[10:11], v[230:231]
	v_pk_mul_f32 v[16:17], v[16:17], v[232:233]
	v_pk_mul_f32 v[12:13], v[12:13], v[234:235]
	v_cvt_pk_bf16_f32 v236, v14, v15
	v_cvt_pk_bf16_f32 v237, v16, v17
	v_cvt_pk_bf16_f32 v238, v10, v11
	v_cvt_pk_bf16_f32 v239, v12, v13
	global_store_dwordx4 v[152:153], v[236:239], off
	s_waitcnt vmcnt(3)
	v_pk_add_f32 v[8:9], v[8:9], v[222:223]
	v_pk_add_f32 v[6:7], v[6:7], v[220:221]
	v_pk_add_f32 v[4:5], v[4:5], v[226:227]
	v_pk_add_f32 v[2:3], v[2:3], v[224:225]
	v_mul_f32_e32 v228, 0x3d372713, v6
	v_mul_f32_e32 v229, 0x3d372713, v7
	v_mul_f32_e32 v230, 0x3d372713, v2
	v_mul_f32_e32 v231, 0x3d372713, v3
	v_mul_f32_e32 v232, 0x3d372713, v8
	v_mul_f32_e32 v233, 0x3d372713, v9
	v_mul_f32_e32 v234, 0x3d372713, v4
	v_mul_f32_e32 v235, 0x3d372713, v5
	v_mul_f32_e32 v228, v6, v228
	v_mul_f32_e32 v229, v7, v229
	v_mul_f32_e32 v230, v2, v230
	v_mul_f32_e32 v231, v3, v231
	v_mul_f32_e32 v232, v8, v232
	v_mul_f32_e32 v233, v9, v233
	v_mul_f32_e32 v234, v4, v234
	v_mul_f32_e32 v235, v5, v235
	v_fma_f32 v228, v6, v228, v6
	v_fma_f32 v229, v7, v229, v7
	v_fma_f32 v230, v2, v230, v2
	v_fma_f32 v231, v3, v231, v3
	v_fma_f32 v232, v8, v232, v8
	v_fma_f32 v233, v9, v233, v9
	v_fma_f32 v234, v4, v234, v4
	v_fma_f32 v235, v5, v235, v5
	v_mul_f32_e32 v228, 0xbfcc422a, v228
	v_mul_f32_e32 v229, 0xbfcc422a, v229
	v_mul_f32_e32 v230, 0xbfcc422a, v230
	v_mul_f32_e32 v231, 0xbfcc422a, v231
	v_mul_f32_e32 v232, 0xbfcc422a, v232
	v_mul_f32_e32 v233, 0xbfcc422a, v233
	v_mul_f32_e32 v234, 0xbfcc422a, v234
	v_mul_f32_e32 v235, 0xbfcc422a, v235
	v_mul_f32_e32 v228, 0x3fb8aa3b, v228
	v_mul_f32_e32 v229, 0x3fb8aa3b, v229
	v_mul_f32_e32 v230, 0x3fb8aa3b, v230
	v_mul_f32_e32 v231, 0x3fb8aa3b, v231
	v_mul_f32_e32 v232, 0x3fb8aa3b, v232
	v_mul_f32_e32 v233, 0x3fb8aa3b, v233
	v_mul_f32_e32 v234, 0x3fb8aa3b, v234
	v_mul_f32_e32 v235, 0x3fb8aa3b, v235
	v_exp_f32_e32 v228, v228
	v_exp_f32_e32 v229, v229
	v_exp_f32_e32 v230, v230
	v_exp_f32_e32 v231, v231
	v_exp_f32_e32 v232, v232
	v_exp_f32_e32 v233, v233
	v_exp_f32_e32 v234, v234
	v_exp_f32_e32 v235, v235
	v_add_f32_e32 v228, 1.0, v228
	v_add_f32_e32 v229, 1.0, v229
	v_add_f32_e32 v230, 1.0, v230
	v_add_f32_e32 v231, 1.0, v231
	v_add_f32_e32 v232, 1.0, v232
	v_add_f32_e32 v233, 1.0, v233
	v_add_f32_e32 v234, 1.0, v234
	v_add_f32_e32 v235, 1.0, v235
	v_rcp_f32_e32 v228, v228
	v_rcp_f32_e32 v229, v229
	v_rcp_f32_e32 v230, v230
	v_rcp_f32_e32 v231, v231
	v_rcp_f32_e32 v232, v232
	v_rcp_f32_e32 v233, v233
	v_rcp_f32_e32 v234, v234
	v_rcp_f32_e32 v235, v235
	v_pk_mul_f32 v[6:7], v[6:7], v[228:229]
	v_pk_mul_f32 v[2:3], v[2:3], v[230:231]
	v_pk_mul_f32 v[8:9], v[8:9], v[232:233]
	v_pk_mul_f32 v[4:5], v[4:5], v[234:235]
	v_cvt_pk_bf16_f32 v236, v6, v7
	v_cvt_pk_bf16_f32 v237, v8, v9
	v_cvt_pk_bf16_f32 v238, v2, v3
	v_cvt_pk_bf16_f32 v239, v4, v5
	global_store_dwordx4 v[246:247], v[236:239], off
	s_waitcnt vmcnt(0)
	s_barrier
